# strategy 4: one static s_setprio 1 for the younger wave half (waves 4-7) across the NSA unit loop, restored to 0 at exit
# speedup vs baseline: 1.0007x; 1.0007x over previous
.LBB0_695:
	s_setprio 0
	s_waitcnt vmcnt(0)
	s_barrier
	s_and_saveexec_b64 s[0:1], s[86:87]
	s_cbranch_execz .LBB0_1081
	v_mov_b32_e32 v0, 0x24000
	s_waitcnt vmcnt(0) expcnt(0) lgkmcnt(0)
	ds_read_b32 v3, v0
	v_mov_b32_e32 v0, 0x24004
	ds_read_b32 v2, v0
	s_waitcnt lgkmcnt(1)
	v_cmp_ne_u32_e32 vcc, 0, v3
	s_cbranch_vccnz .LBB0_1049
	s_mov_b32 s2, 1
	s_branch .LBB0_1037

.LBB0_700:
	s_lshr_b32 s0, s42, 5
	s_xor_b32 s0, s0, s42
	s_lshr_b32 s2, s42, 1
	s_and_b32 s45, s0, 1
	s_cmp_lt_u32 s42, 64
	v_readlane_b32 s0, v252, 61
	v_readlane_b32 s1, v252, 62
	s_cselect_b32 s46, s1, s0
	s_or_b32 s0, s46, 31
	s_bfe_u32 s1, s42, 0x50001
	v_mov_b32_e32 v67, v194
	s_sub_i32 s39, s0, s1
	s_lshl_b32 s47, s39, 5
	v_readfirstlane_b32 s0, v67
	s_ashr_i32 s80, s0, 6
	s_cmp_ge_u32 s80, 4
	s_cbranch_scc0 .Lnsa_prio_lo
	s_setprio 1
.Lnsa_prio_lo:
	s_lshl_b32 s43, s80, 2
	v_readlane_b32 s48, v251, 54
	s_add_i32 s44, s43, s47
	v_bfe_u32 v120, v67, 2, 2
	s_waitcnt vmcnt(5)
	v_and_b32_e32 v52, 3, v67
	v_readlane_b32 s54, v251, 60
	v_readlane_b32 s55, v251, 61
	v_or_b32_e32 v103, s44, v120
	v_lshl_or_b32 v22, s45, 2, v52
	v_mov_b64_e32 v[2:3], s[54:55]
	v_mad_i64_i32 v[2:3], s[0:1], v103, s3, v[2:3]
	v_lshlrev_b32_e32 v0, 7, v22
	v_mul_u32_u24_e32 v12, 3, v22
	v_lshl_add_u64 v[4:5], v[2:3], 0, v[0:1]
	s_mov_b64 s[0:1], 0x1400
	v_lshlrev_b32_e32 v12, 1, v12
	v_mov_b32_e32 v13, v1
	v_lshl_add_u64 v[92:93], v[4:5], 0, s[0:1]
	v_lshl_add_u64 v[2:3], v[2:3], 0, v[12:13]
	s_mov_b64 s[0:1], 0x1e00
	v_and_b32_e32 v0, 48, v67
	v_lshl_add_u64 v[12:13], v[2:3], 0, s[0:1]
	v_add_co_u32_e32 v2, vcc, 0x1000, v2
	v_lshl_add_u64 v[8:9], v[92:93], 0, v[0:1]
	s_nop 0
	v_addc_co_u32_e32 v3, vcc, 0, v3, vcc
	global_load_dwordx4 v[4:7], v[8:9], off
	s_nop 0
	global_load_dwordx4 v[8:11], v[8:9], off offset:64
	s_nop 0
	global_load_dword v94, v[2:3], off offset:3584
	global_load_ushort v95, v[12:13], off offset:4
	v_and_b32_e32 v86, 63, v67
	v_bfe_u32 v21, v67, 4, 2
	s_mul_i32 s81, s80, 0x2100
	v_and_b32_e32 v54, 15, v67
	v_lshlrev_b32_e32 v53, 3, v21
	v_mov_b32_e32 v244, 0
	v_mov_b32_e32 v245, 0
	v_mov_b32_e32 v246, 0
	v_mov_b32_e32 v247, 0
	v_lshl_add_u32 v2, v86, 4, s81
	v_lshl_add_u32 v3, v54, 2, s81
	v_readlane_b32 s49, v251, 55
	v_readlane_b32 s50, v251, 56
	v_readlane_b32 s51, v251, 57
	v_readlane_b32 s52, v251, 58
	v_readlane_b32 s53, v251, 59
	v_readlane_b32 s56, v251, 62
	v_readlane_b32 s57, v251, 63
	v_readlane_b32 s58, v252, 0
	v_readlane_b32 s59, v252, 1
	v_readlane_b32 s60, v252, 2
	v_readlane_b32 s61, v252, 3
	v_readlane_b32 s62, v252, 4
	v_readlane_b32 s63, v252, 5
	ds_write_b128 v2, v[244:247]
	ds_write_b128 v2, v[244:247] offset:1024
	ds_write_b128 v2, v[244:247] offset:2048
	ds_write_b128 v2, v[244:247] offset:3072
	ds_write_b128 v2, v[244:247] offset:4096
	ds_write_b128 v2, v[244:247] offset:5120
	ds_write_b128 v2, v[244:247] offset:6144
	ds_write_b128 v2, v[244:247] offset:7168
	ds_write_b32 v3, v1 offset:8192
	s_lshl_b32 s0, s39, 1
	s_add_i32 s0, s0, 64
	v_readlane_b32 s48, v251, 54
	v_lshlrev_b32_e32 v3, 3, v67
	v_ashrrev_i32_e32 v2, 3, v67
	s_lshr_b32 s12, s0, 6
	s_lshl_b32 s88, s45, 17
	v_readlane_b32 s60, v252, 2
	v_and_b32_e32 v20, 56, v3
	v_readlane_b32 s61, v252, 3
	s_add_u32 s0, s60, s88
	v_ashrrev_i32_e32 v3, 31, v2
	s_addc_u32 s1, s61, 0
	v_lshlrev_b64 v[44:45], 7, v[2:3]
	v_lshl_add_u64 v[12:13], s[0:1], 0, v[44:45]
	v_lshlrev_b32_e32 v80, 1, v20
	v_mov_b32_e32 v81, v1
	s_add_i32 s0, s12, -1
	s_mov_b32 s1, s89
	v_lshl_add_u64 v[36:37], v[12:13], 0, v[80:81]
	s_lshl_b64 s[0:1], s[0:1], 13
	v_lshl_add_u64 v[12:13], v[36:37], 0, s[0:1]
	global_load_dwordx4 v[12:15], v[12:13], off
	s_cmp_gt_u32 s39, 31
	s_cselect_b64 s[0:1], -1, 0
	s_cmp_lt_u32 s39, 32
	v_readlane_b32 s49, v251, 55
	v_readlane_b32 s50, v251, 56
	v_readlane_b32 s51, v251, 57
	v_readlane_b32 s52, v251, 58
	v_readlane_b32 s53, v251, 59
	v_readlane_b32 s54, v251, 60
	v_readlane_b32 s55, v251, 61
	v_readlane_b32 s56, v251, 62
	v_readlane_b32 s57, v251, 63
	v_readlane_b32 s58, v252, 0
	v_readlane_b32 s59, v252, 1
	v_readlane_b32 s62, v252, 4
	v_readlane_b32 s63, v252, 5
	s_cbranch_scc1 .LBB0_704
	s_lshl_b32 s4, s12, 13
	s_mov_b32 s5, s89
	v_lshl_add_u64 v[16:17], v[36:37], 0, s[4:5]
	v_add_co_u32_e32 v16, vcc, 0xffffc000, v16
	s_nop 1
	v_addc_co_u32_e32 v17, vcc, -1, v17, vcc
	global_load_dwordx4 v[16:19], v[16:17], off
	s_branch .LBB0_705
